# SSD part 2: the 16 STATES (S_in) loads per thread issued together instead of one load + vmcnt(0) at a time
# speedup vs baseline: 1.0163x; 1.0163x over previous
; #define LAS __attribute__((address_space(3)))
; DI unsigned pk2(float lo, float hi) { f32x2_t v = {lo, hi}; bf16x2_t b = __builtin_convertvector(v, bf16x2_t); return __builtin_bit_cast(unsigned, b); }
; DI void ssd_part2_unit(int u, const bf16* PROJ, const float* DT, const float* cw, const float* cb, const float* a_log_l, const float* dskip_l, const float* snw_l,
;                        const float* STATES, bf16* YC, LAS unsigned char* ldsu, int tid, int wave, int lane) {
;     ...
; #pragma unroll 4
;     for (int k = 0; k < 16; ++k) { const int idx = tid + 512 * k, combo = idx >> 11, within = idx & 2047, pp = within >> 5, n4 = within & 31;
;         const int hh = combo >> 1, dir = combo & 1, h = 2 * grp + hh;
;         const f32x4 sv = *(const f32x4*)(STATES + ((size_t)(((b * 16 + c) * 4 + h) * 2 + dir) * 64 + pp) * 128 + n4 * 4);
;         u32x2 w; w.x = pk2(sv[0], sv[1]); w.y = pk2(sv[2], sv[3]);
;         *(LAS u32x2*)(lds + combo * (64 * IMG_PITCH) + pp * IMG_PITCH + n4 * 8) = w; }
.LBB0_502:
	v_mov_b32_e32 v209, v189
	v_mov_b32_e32 v76, v193
	v_ashrrev_i32_e32 v4, 12, v76
	v_bfe_u32 v5, v76, 11, 1
	v_add_u32_e32 v4, s0, v4
	v_lshl_or_b32 v12, v4, 1, v5
	v_ashrrev_i32_e32 v13, 31, v12
	v_lshlrev_b64 v[12:13], 15, v[12:13]
	v_lshl_add_u64 v[12:13], s[12:13], 0, v[12:13]
	v_bfe_u32 v6, v76, 5, 6
	v_lshlrev_b32_e32 v188, 9, v6
	v_lshl_add_u64 v[12:13], v[12:13], 0, v[188:189]
	v_lshl_add_u64 v[12:13], v[12:13], 0, v[208:209]
	global_load_dwordx4 v[12:15], v[12:13], off
	v_add_u32_e32 v77, 0x200, v193
	v_ashrrev_i32_e32 v4, 12, v77
	v_bfe_u32 v5, v77, 11, 1
	v_add_u32_e32 v4, s0, v4
	v_lshl_or_b32 v16, v4, 1, v5
	v_ashrrev_i32_e32 v17, 31, v16
	v_lshlrev_b64 v[16:17], 15, v[16:17]
	v_lshl_add_u64 v[16:17], s[12:13], 0, v[16:17]
	v_bfe_u32 v6, v77, 5, 6
	v_lshlrev_b32_e32 v188, 9, v6
	v_lshl_add_u64 v[16:17], v[16:17], 0, v[188:189]
	v_lshl_add_u64 v[16:17], v[16:17], 0, v[208:209]
	global_load_dwordx4 v[16:19], v[16:17], off
	v_add_u32_e32 v78, 0x400, v193
	v_ashrrev_i32_e32 v4, 12, v78
	v_bfe_u32 v5, v78, 11, 1
	v_add_u32_e32 v4, s0, v4
	v_lshl_or_b32 v20, v4, 1, v5
	v_ashrrev_i32_e32 v21, 31, v20
	v_lshlrev_b64 v[20:21], 15, v[20:21]
	v_lshl_add_u64 v[20:21], s[12:13], 0, v[20:21]
	v_bfe_u32 v6, v78, 5, 6
	v_lshlrev_b32_e32 v188, 9, v6
	v_lshl_add_u64 v[20:21], v[20:21], 0, v[188:189]
	v_lshl_add_u64 v[20:21], v[20:21], 0, v[208:209]
	global_load_dwordx4 v[20:23], v[20:21], off
	v_add_u32_e32 v79, 0x600, v193
	v_ashrrev_i32_e32 v4, 12, v79
	v_bfe_u32 v5, v79, 11, 1
	v_add_u32_e32 v4, s0, v4
	v_lshl_or_b32 v24, v4, 1, v5
	v_ashrrev_i32_e32 v25, 31, v24
	v_lshlrev_b64 v[24:25], 15, v[24:25]
	v_lshl_add_u64 v[24:25], s[12:13], 0, v[24:25]
	v_bfe_u32 v6, v79, 5, 6
	v_lshlrev_b32_e32 v188, 9, v6
	v_lshl_add_u64 v[24:25], v[24:25], 0, v[188:189]
	v_lshl_add_u64 v[24:25], v[24:25], 0, v[208:209]
	global_load_dwordx4 v[24:27], v[24:25], off
	v_add_u32_e32 v80, 0x800, v193
	v_ashrrev_i32_e32 v4, 12, v80
	v_bfe_u32 v5, v80, 11, 1
	v_add_u32_e32 v4, s0, v4
	v_lshl_or_b32 v28, v4, 1, v5
	v_ashrrev_i32_e32 v29, 31, v28
	v_lshlrev_b64 v[28:29], 15, v[28:29]
	v_lshl_add_u64 v[28:29], s[12:13], 0, v[28:29]
	v_bfe_u32 v6, v80, 5, 6
	v_lshlrev_b32_e32 v188, 9, v6
	v_lshl_add_u64 v[28:29], v[28:29], 0, v[188:189]
	v_lshl_add_u64 v[28:29], v[28:29], 0, v[208:209]
	global_load_dwordx4 v[28:31], v[28:29], off
	v_add_u32_e32 v81, 0xa00, v193
	v_ashrrev_i32_e32 v4, 12, v81
	v_bfe_u32 v5, v81, 11, 1
	v_add_u32_e32 v4, s0, v4
	v_lshl_or_b32 v32, v4, 1, v5
	v_ashrrev_i32_e32 v33, 31, v32
	v_lshlrev_b64 v[32:33], 15, v[32:33]
	v_lshl_add_u64 v[32:33], s[12:13], 0, v[32:33]
	v_bfe_u32 v6, v81, 5, 6
	v_lshlrev_b32_e32 v188, 9, v6
	v_lshl_add_u64 v[32:33], v[32:33], 0, v[188:189]
	v_lshl_add_u64 v[32:33], v[32:33], 0, v[208:209]
	global_load_dwordx4 v[32:35], v[32:33], off
	v_add_u32_e32 v82, 0xc00, v193
	v_ashrrev_i32_e32 v4, 12, v82
	v_bfe_u32 v5, v82, 11, 1
	v_add_u32_e32 v4, s0, v4
	v_lshl_or_b32 v36, v4, 1, v5
	v_ashrrev_i32_e32 v37, 31, v36
	v_lshlrev_b64 v[36:37], 15, v[36:37]
	v_lshl_add_u64 v[36:37], s[12:13], 0, v[36:37]
	v_bfe_u32 v6, v82, 5, 6
	v_lshlrev_b32_e32 v188, 9, v6
	v_lshl_add_u64 v[36:37], v[36:37], 0, v[188:189]
	v_lshl_add_u64 v[36:37], v[36:37], 0, v[208:209]
	global_load_dwordx4 v[36:39], v[36:37], off
	v_add_u32_e32 v83, 0xe00, v193
	v_ashrrev_i32_e32 v4, 12, v83
	v_bfe_u32 v5, v83, 11, 1
	v_add_u32_e32 v4, s0, v4
	v_lshl_or_b32 v40, v4, 1, v5
	v_ashrrev_i32_e32 v41, 31, v40
	v_lshlrev_b64 v[40:41], 15, v[40:41]
	v_lshl_add_u64 v[40:41], s[12:13], 0, v[40:41]
	v_bfe_u32 v6, v83, 5, 6
	v_lshlrev_b32_e32 v188, 9, v6
	v_lshl_add_u64 v[40:41], v[40:41], 0, v[188:189]
	v_lshl_add_u64 v[40:41], v[40:41], 0, v[208:209]
	global_load_dwordx4 v[40:43], v[40:41], off
	v_add_u32_e32 v84, 0x1000, v193
	v_ashrrev_i32_e32 v4, 12, v84
	v_bfe_u32 v5, v84, 11, 1
	v_add_u32_e32 v4, s0, v4
	v_lshl_or_b32 v44, v4, 1, v5
	v_ashrrev_i32_e32 v45, 31, v44
	v_lshlrev_b64 v[44:45], 15, v[44:45]
	v_lshl_add_u64 v[44:45], s[12:13], 0, v[44:45]
	v_bfe_u32 v6, v84, 5, 6
	v_lshlrev_b32_e32 v188, 9, v6
	v_lshl_add_u64 v[44:45], v[44:45], 0, v[188:189]
	v_lshl_add_u64 v[44:45], v[44:45], 0, v[208:209]
	global_load_dwordx4 v[44:47], v[44:45], off
	v_add_u32_e32 v85, 0x1200, v193
	v_ashrrev_i32_e32 v4, 12, v85
	v_bfe_u32 v5, v85, 11, 1
	v_add_u32_e32 v4, s0, v4
	v_lshl_or_b32 v48, v4, 1, v5
	v_ashrrev_i32_e32 v49, 31, v48
	v_lshlrev_b64 v[48:49], 15, v[48:49]
	v_lshl_add_u64 v[48:49], s[12:13], 0, v[48:49]
	v_bfe_u32 v6, v85, 5, 6
	v_lshlrev_b32_e32 v188, 9, v6
	v_lshl_add_u64 v[48:49], v[48:49], 0, v[188:189]
	v_lshl_add_u64 v[48:49], v[48:49], 0, v[208:209]
	global_load_dwordx4 v[48:51], v[48:49], off
	v_add_u32_e32 v86, 0x1400, v193
	v_ashrrev_i32_e32 v4, 12, v86
	v_bfe_u32 v5, v86, 11, 1
	v_add_u32_e32 v4, s0, v4
	v_lshl_or_b32 v52, v4, 1, v5
	v_ashrrev_i32_e32 v53, 31, v52
	v_lshlrev_b64 v[52:53], 15, v[52:53]
	v_lshl_add_u64 v[52:53], s[12:13], 0, v[52:53]
	v_bfe_u32 v6, v86, 5, 6
	v_lshlrev_b32_e32 v188, 9, v6
	v_lshl_add_u64 v[52:53], v[52:53], 0, v[188:189]
	v_lshl_add_u64 v[52:53], v[52:53], 0, v[208:209]
	global_load_dwordx4 v[52:55], v[52:53], off
	v_add_u32_e32 v87, 0x1600, v193
	v_ashrrev_i32_e32 v4, 12, v87
	v_bfe_u32 v5, v87, 11, 1
	v_add_u32_e32 v4, s0, v4
	v_lshl_or_b32 v56, v4, 1, v5
	v_ashrrev_i32_e32 v57, 31, v56
	v_lshlrev_b64 v[56:57], 15, v[56:57]
	v_lshl_add_u64 v[56:57], s[12:13], 0, v[56:57]
	v_bfe_u32 v6, v87, 5, 6
	v_lshlrev_b32_e32 v188, 9, v6
	v_lshl_add_u64 v[56:57], v[56:57], 0, v[188:189]
	v_lshl_add_u64 v[56:57], v[56:57], 0, v[208:209]
	global_load_dwordx4 v[56:59], v[56:57], off
	v_add_u32_e32 v88, 0x1800, v193
; #define LAS __attribute__((address_space(3)))
; DI unsigned pk2(float lo, float hi) { f32x2_t v = {lo, hi}; bf16x2_t b = __builtin_convertvector(v, bf16x2_t); return __builtin_bit_cast(unsigned, b); }
; DI void ssd_part2_unit(int u, const bf16* PROJ, const float* DT, const float* cw, const float* cb, const float* a_log_l, const float* dskip_l, const float* snw_l,
;                        const float* STATES, bf16* YC, LAS unsigned char* ldsu, int tid, int wave, int lane) {
;     ...
; #pragma unroll 4
;     for (int k = 0; k < 16; ++k) { const int idx = tid + 512 * k, combo = idx >> 11, within = idx & 2047, pp = within >> 5, n4 = within & 31;
;         const int hh = combo >> 1, dir = combo & 1, h = 2 * grp + hh;
;         const f32x4 sv = *(const f32x4*)(STATES + ((size_t)(((b * 16 + c) * 4 + h) * 2 + dir) * 64 + pp) * 128 + n4 * 4);
;         u32x2 w; w.x = pk2(sv[0], sv[1]); w.y = pk2(sv[2], sv[3]);
;         *(LAS u32x2*)(lds + combo * (64 * IMG_PITCH) + pp * IMG_PITCH + n4 * 8) = w; }
;     __syncthreads();
	v_ashrrev_i32_e32 v4, 12, v88
	v_bfe_u32 v5, v88, 11, 1
	v_add_u32_e32 v4, s0, v4
	v_lshl_or_b32 v60, v4, 1, v5
	v_ashrrev_i32_e32 v61, 31, v60
	v_lshlrev_b64 v[60:61], 15, v[60:61]
	v_lshl_add_u64 v[60:61], s[12:13], 0, v[60:61]
	v_bfe_u32 v6, v88, 5, 6
	v_lshlrev_b32_e32 v188, 9, v6
	v_lshl_add_u64 v[60:61], v[60:61], 0, v[188:189]
	v_lshl_add_u64 v[60:61], v[60:61], 0, v[208:209]
	global_load_dwordx4 v[60:63], v[60:61], off
	v_add_u32_e32 v89, 0x1a00, v193
	v_ashrrev_i32_e32 v4, 12, v89
	v_bfe_u32 v5, v89, 11, 1
	v_add_u32_e32 v4, s0, v4
	v_lshl_or_b32 v64, v4, 1, v5
	v_ashrrev_i32_e32 v65, 31, v64
	v_lshlrev_b64 v[64:65], 15, v[64:65]
	v_lshl_add_u64 v[64:65], s[12:13], 0, v[64:65]
	v_bfe_u32 v6, v89, 5, 6
	v_lshlrev_b32_e32 v188, 9, v6
	v_lshl_add_u64 v[64:65], v[64:65], 0, v[188:189]
	v_lshl_add_u64 v[64:65], v[64:65], 0, v[208:209]
	global_load_dwordx4 v[64:67], v[64:65], off
	v_add_u32_e32 v90, 0x1c00, v193
	v_ashrrev_i32_e32 v4, 12, v90
	v_bfe_u32 v5, v90, 11, 1
	v_add_u32_e32 v4, s0, v4
	v_lshl_or_b32 v68, v4, 1, v5
	v_ashrrev_i32_e32 v69, 31, v68
	v_lshlrev_b64 v[68:69], 15, v[68:69]
	v_lshl_add_u64 v[68:69], s[12:13], 0, v[68:69]
	v_bfe_u32 v6, v90, 5, 6
	v_lshlrev_b32_e32 v188, 9, v6
	v_lshl_add_u64 v[68:69], v[68:69], 0, v[188:189]
	v_lshl_add_u64 v[68:69], v[68:69], 0, v[208:209]
	global_load_dwordx4 v[68:71], v[68:69], off
	v_add_u32_e32 v91, 0x1e00, v193
	v_ashrrev_i32_e32 v4, 12, v91
	v_bfe_u32 v5, v91, 11, 1
	v_add_u32_e32 v4, s0, v4
	v_lshl_or_b32 v72, v4, 1, v5
	v_ashrrev_i32_e32 v73, 31, v72
	v_lshlrev_b64 v[72:73], 15, v[72:73]
	v_lshl_add_u64 v[72:73], s[12:13], 0, v[72:73]
	v_bfe_u32 v6, v91, 5, 6
	v_lshlrev_b32_e32 v188, 9, v6
	v_lshl_add_u64 v[72:73], v[72:73], 0, v[188:189]
	v_lshl_add_u64 v[72:73], v[72:73], 0, v[208:209]
	global_load_dwordx4 v[72:75], v[72:73], off
	s_waitcnt vmcnt(15)
	v_cvt_pk_bf16_f32 v12, v12, v13
	v_cvt_pk_bf16_f32 v13, v14, v15
	v_ashrrev_i32_e32 v4, 11, v76
	v_bfe_u32 v6, v76, 5, 6
	v_mad_i32_i24 v4, v4, s72, 0
	v_mul_u32_u24_e32 v7, 0x110, v6
	v_add3_u32 v4, v4, v7, v212
	ds_write_b64 v4, v[12:13]
	s_waitcnt vmcnt(14)
	v_cvt_pk_bf16_f32 v16, v16, v17
	v_cvt_pk_bf16_f32 v17, v18, v19
	v_ashrrev_i32_e32 v4, 11, v77
	v_bfe_u32 v6, v77, 5, 6
	v_mad_i32_i24 v4, v4, s72, 0
	v_mul_u32_u24_e32 v7, 0x110, v6
	v_add3_u32 v4, v4, v7, v212
	ds_write_b64 v4, v[16:17]
	s_waitcnt vmcnt(13)
	v_cvt_pk_bf16_f32 v20, v20, v21
	v_cvt_pk_bf16_f32 v21, v22, v23
	v_ashrrev_i32_e32 v4, 11, v78
	v_bfe_u32 v6, v78, 5, 6
	v_mad_i32_i24 v4, v4, s72, 0
	v_mul_u32_u24_e32 v7, 0x110, v6
	v_add3_u32 v4, v4, v7, v212
	ds_write_b64 v4, v[20:21]
	s_waitcnt vmcnt(12)
	v_cvt_pk_bf16_f32 v24, v24, v25
	v_cvt_pk_bf16_f32 v25, v26, v27
	v_ashrrev_i32_e32 v4, 11, v79
	v_bfe_u32 v6, v79, 5, 6
	v_mad_i32_i24 v4, v4, s72, 0
	v_mul_u32_u24_e32 v7, 0x110, v6
	v_add3_u32 v4, v4, v7, v212
	ds_write_b64 v4, v[24:25]
	s_waitcnt vmcnt(11)
	v_cvt_pk_bf16_f32 v28, v28, v29
	v_cvt_pk_bf16_f32 v29, v30, v31
	v_ashrrev_i32_e32 v4, 11, v80
	v_bfe_u32 v6, v80, 5, 6
	v_mad_i32_i24 v4, v4, s72, 0
	v_mul_u32_u24_e32 v7, 0x110, v6
	v_add3_u32 v4, v4, v7, v212
	ds_write_b64 v4, v[28:29]
	s_waitcnt vmcnt(10)
	v_cvt_pk_bf16_f32 v32, v32, v33
	v_cvt_pk_bf16_f32 v33, v34, v35
	v_ashrrev_i32_e32 v4, 11, v81
	v_bfe_u32 v6, v81, 5, 6
	v_mad_i32_i24 v4, v4, s72, 0
	v_mul_u32_u24_e32 v7, 0x110, v6
	v_add3_u32 v4, v4, v7, v212
	ds_write_b64 v4, v[32:33]
	s_waitcnt vmcnt(9)
	v_cvt_pk_bf16_f32 v36, v36, v37
	v_cvt_pk_bf16_f32 v37, v38, v39
	v_ashrrev_i32_e32 v4, 11, v82
	v_bfe_u32 v6, v82, 5, 6
	v_mad_i32_i24 v4, v4, s72, 0
	v_mul_u32_u24_e32 v7, 0x110, v6
	v_add3_u32 v4, v4, v7, v212
	ds_write_b64 v4, v[36:37]
	s_waitcnt vmcnt(8)
	v_cvt_pk_bf16_f32 v40, v40, v41
	v_cvt_pk_bf16_f32 v41, v42, v43
	v_ashrrev_i32_e32 v4, 11, v83
	v_bfe_u32 v6, v83, 5, 6
	v_mad_i32_i24 v4, v4, s72, 0
	v_mul_u32_u24_e32 v7, 0x110, v6
	v_add3_u32 v4, v4, v7, v212
	ds_write_b64 v4, v[40:41]
	s_waitcnt vmcnt(7)
	v_cvt_pk_bf16_f32 v44, v44, v45
	v_cvt_pk_bf16_f32 v45, v46, v47
	v_ashrrev_i32_e32 v4, 11, v84
	v_bfe_u32 v6, v84, 5, 6
	v_mad_i32_i24 v4, v4, s72, 0
	v_mul_u32_u24_e32 v7, 0x110, v6
	v_add3_u32 v4, v4, v7, v212
	ds_write_b64 v4, v[44:45]
	s_waitcnt vmcnt(6)
	v_cvt_pk_bf16_f32 v48, v48, v49
	v_cvt_pk_bf16_f32 v49, v50, v51
	v_ashrrev_i32_e32 v4, 11, v85
	v_bfe_u32 v6, v85, 5, 6
	v_mad_i32_i24 v4, v4, s72, 0
	v_mul_u32_u24_e32 v7, 0x110, v6
	v_add3_u32 v4, v4, v7, v212
	ds_write_b64 v4, v[48:49]
	s_waitcnt vmcnt(5)
	v_cvt_pk_bf16_f32 v52, v52, v53
	v_cvt_pk_bf16_f32 v53, v54, v55
	v_ashrrev_i32_e32 v4, 11, v86
	v_bfe_u32 v6, v86, 5, 6
	v_mad_i32_i24 v4, v4, s72, 0
	v_mul_u32_u24_e32 v7, 0x110, v6
	v_add3_u32 v4, v4, v7, v212
	ds_write_b64 v4, v[52:53]
	s_waitcnt vmcnt(4)
	v_cvt_pk_bf16_f32 v56, v56, v57
	v_cvt_pk_bf16_f32 v57, v58, v59
	v_ashrrev_i32_e32 v4, 11, v87
	v_bfe_u32 v6, v87, 5, 6
	v_mad_i32_i24 v4, v4, s72, 0
	v_mul_u32_u24_e32 v7, 0x110, v6
	v_add3_u32 v4, v4, v7, v212
	ds_write_b64 v4, v[56:57]
	s_waitcnt vmcnt(3)
	v_cvt_pk_bf16_f32 v60, v60, v61
	v_cvt_pk_bf16_f32 v61, v62, v63
	v_ashrrev_i32_e32 v4, 11, v88
	v_bfe_u32 v6, v88, 5, 6
	v_mad_i32_i24 v4, v4, s72, 0
	v_mul_u32_u24_e32 v7, 0x110, v6
	v_add3_u32 v4, v4, v7, v212
	ds_write_b64 v4, v[60:61]
	s_waitcnt vmcnt(2)
	v_cvt_pk_bf16_f32 v64, v64, v65
	v_cvt_pk_bf16_f32 v65, v66, v67
	v_ashrrev_i32_e32 v4, 11, v89
	v_bfe_u32 v6, v89, 5, 6
	v_mad_i32_i24 v4, v4, s72, 0
	v_mul_u32_u24_e32 v7, 0x110, v6
	v_add3_u32 v4, v4, v7, v212
	ds_write_b64 v4, v[64:65]
	s_waitcnt vmcnt(1)
	v_cvt_pk_bf16_f32 v68, v68, v69
	v_cvt_pk_bf16_f32 v69, v70, v71
	v_ashrrev_i32_e32 v4, 11, v90
	v_bfe_u32 v6, v90, 5, 6
	v_mad_i32_i24 v4, v4, s72, 0
	v_mul_u32_u24_e32 v7, 0x110, v6
	v_add3_u32 v4, v4, v7, v212
	ds_write_b64 v4, v[68:69]
	s_waitcnt vmcnt(0)
	v_cvt_pk_bf16_f32 v72, v72, v73
	v_cvt_pk_bf16_f32 v73, v74, v75
	v_ashrrev_i32_e32 v4, 11, v91
	v_bfe_u32 v6, v91, 5, 6
	v_mad_i32_i24 v4, v4, s72, 0
	v_mul_u32_u24_e32 v7, 0x110, v6
	v_add3_u32 v4, v4, v7, v212
	ds_write_b64 v4, v[72:73]
	v_add_u32_e32 v48, v215, v216
	s_waitcnt lgkmcnt(0)
	s_barrier
; #define LAS __attribute__((address_space(3)))
; #define MFMA16(a, b, c) __builtin_amdgcn_mfma_f32_16x16x32_bf16((a), (b), (c), 0, 0, 0)
; DI void ssd_part2_unit(int u, const bf16* PROJ, const float* DT, const float* cw, const float* cb, const float* a_log_l, const float* dskip_l, const float* snw_l,
;                        const float* STATES, bf16* YC, LAS unsigned char* ldsu, int tid, int wave, int lane) {
;     ...
;     const int r = lane & 15, g = lane >> 4, q = (lane & 15) >> 2, p = lane & 3;
;     const int l0 = 16 * wave, lq = l0 + r;
;     bf16x8 cq[4];
; #pragma unroll
;     for (int ks = 0; ks < 4; ++ks) cq[ks] = *(const LAS bf16x8*)(CM + lq * IMG_PITCH + 64 * ks + 16 * g);
;     f32x4 acc[2][4];
; #pragma unroll
;     for (int hh = 0; hh < 2; ++hh)
; #pragma unroll
;         for (int pt = 0; pt < 4; ++pt) acc[hh][pt] = (f32x4){0.f, 0.f, 0.f, 0.f};
; #pragma unroll
;     for (int combo = 0; combo < 4; ++combo) {
;         const int hh = combo >> 1;
;         const float eg = __expf(gtab[combo * 128 + lq]);
; #pragma unroll
;         for (int pt = 0; pt < 4; ++pt) {
;             f32x4 tmp = (f32x4){0.f, 0.f, 0.f, 0.f};
; #pragma unroll
;             for (int ks = 0; ks < 4; ++ks) { const bf16x8 af = *(const LAS bf16x8*)(lds + combo * (64 * IMG_PITCH) + (16 * pt + r) * IMG_PITCH + 64 * ks + 16 * g); tmp = MFMA16(af, cq[ks], tmp); }
;             acc[hh][pt] += tmp * eg;
;         }
;     }
	ds_read_b128 v[16:19], v228
	ds_read_b128 v[20:23], v228 offset:64
	ds_read_b128 v[24:27], v228 offset:128
	ds_read_b128 v[28:31], v228 offset:192
	ds_read2st64_b32 v[44:45], v214 offset1:2
	ds_read_b128 v[4:7], v48
	ds_read_b128 v[8:11], v48 offset:64
	s_lshl_b32 s34, s57, 7
	s_mov_b64 s[0:1], 0x1800
	v_add_u32_e32 v102, s75, v219
	s_waitcnt lgkmcnt(1)
	v_mfma_f32_16x16x32_bf16 v[4:7], v[4:7], v[16:19], 0
	ds_read_b128 v[12:15], v48 offset:4416
	v_lshlrev_b32_e32 v188, 6, v102
	ds_read_b128 v[32:35], v48 offset:8768
	s_waitcnt lgkmcnt(2)
	v_mfma_f32_16x16x32_bf16 v[4:7], v[8:11], v[20:23], v[4:7]
	ds_read_b128 v[8:11], v48 offset:128
	ds_read_b128 v[40:43], v48 offset:17472
	ds_read_b128 v[50:53], v48 offset:21824
	s_waitcnt lgkmcnt(2)
	v_mfma_f32_16x16x32_bf16 v[4:7], v[8:11], v[24:27], v[4:7]
	ds_read_b128 v[8:11], v48 offset:192
	ds_read_b128 v[54:57], v48 offset:26176
	ds_read_b128 v[36:39], v229 offset:64
	s_waitcnt lgkmcnt(2)
	v_mfma_f32_16x16x32_bf16 v[4:7], v[8:11], v[28:31], v[4:7]
	ds_read_b128 v[8:11], v48 offset:4352
	s_waitcnt lgkmcnt(0)
	v_mfma_f32_16x16x32_bf16 v[8:11], v[8:11], v[16:19], 0
	v_mfma_f32_16x16x32_bf16 v[8:11], v[12:15], v[20:23], v[8:11]
	ds_read_b128 v[12:15], v48 offset:4480
	s_waitcnt lgkmcnt(0)
	v_mfma_f32_16x16x32_bf16 v[8:11], v[12:15], v[24:27], v[8:11]
	ds_read_b128 v[12:15], v48 offset:4544
	s_waitcnt lgkmcnt(0)
	v_mfma_f32_16x16x32_bf16 v[8:11], v[12:15], v[28:31], v[8:11]
	ds_read_b128 v[12:15], v48 offset:8704
	s_waitcnt lgkmcnt(0)
	v_mfma_f32_16x16x32_bf16 v[12:15], v[12:15], v[16:19], 0
	v_mfma_f32_16x16x32_bf16 v[12:15], v[32:35], v[20:23], v[12:15]
	ds_read_b128 v[32:35], v48 offset:8832
	s_waitcnt lgkmcnt(0)
	v_mfma_f32_16x16x32_bf16 v[12:15], v[32:35], v[24:27], v[12:15]
	ds_read_b128 v[32:35], v48 offset:8896
	s_waitcnt lgkmcnt(0)
	v_mfma_f32_16x16x32_bf16 v[12:15], v[32:35], v[28:31], v[12:15]
	ds_read_b128 v[32:35], v229
	s_waitcnt lgkmcnt(0)
	v_mfma_f32_16x16x32_bf16 v[32:35], v[32:35], v[16:19], 0
	v_mfma_f32_16x16x32_bf16 v[32:35], v[36:39], v[20:23], v[32:35]
	ds_read_b128 v[36:39], v229 offset:128
	s_waitcnt lgkmcnt(0)
	v_mfma_f32_16x16x32_bf16 v[32:35], v[36:39], v[24:27], v[32:35]
	ds_read_b128 v[36:39], v229 offset:192
	s_waitcnt lgkmcnt(0)
	v_mfma_f32_16x16x32_bf16 v[32:35], v[36:39], v[28:31], v[32:35]
	ds_read_b128 v[36:39], v48 offset:17408
	s_waitcnt lgkmcnt(0)
	v_mfma_f32_16x16x32_bf16 v[36:39], v[36:39], v[16:19], 0
	v_mfma_f32_16x16x32_bf16 v[36:39], v[40:43], v[20:23], v[36:39]
	ds_read_b128 v[40:43], v48 offset:17536
	s_waitcnt lgkmcnt(0)
	v_mfma_f32_16x16x32_bf16 v[36:39], v[40:43], v[24:27], v[36:39]
	ds_read_b128 v[40:43], v48 offset:17600
	s_waitcnt lgkmcnt(0)
	v_mfma_f32_16x16x32_bf16 v[36:39], v[40:43], v[28:31], v[36:39]
	ds_read_b128 v[40:43], v48 offset:21760
	s_waitcnt lgkmcnt(0)
	v_mfma_f32_16x16x32_bf16 v[40:43], v[40:43], v[16:19], 0
	v_mfma_f32_16x16x32_bf16 v[40:43], v[50:53], v[20:23], v[40:43]
	ds_read_b128 v[50:53], v48 offset:21888
	s_waitcnt lgkmcnt(0)
	v_mfma_f32_16x16x32_bf16 v[40:43], v[50:53], v[24:27], v[40:43]
	ds_read_b128 v[50:53], v48 offset:21952
	s_waitcnt lgkmcnt(0)
	v_mfma_f32_16x16x32_bf16 v[40:43], v[50:53], v[28:31], v[40:43]
	ds_read_b128 v[50:53], v48 offset:26112
	s_waitcnt lgkmcnt(0)
	v_mfma_f32_16x16x32_bf16 v[50:53], v[50:53], v[16:19], 0
	v_mfma_f32_16x16x32_bf16 v[50:53], v[54:57], v[20:23], v[50:53]
	ds_read_b128 v[54:57], v48 offset:26240
	s_waitcnt lgkmcnt(0)
	v_mfma_f32_16x16x32_bf16 v[50:53], v[54:57], v[24:27], v[50:53]
	ds_read_b128 v[54:57], v48 offset:26304
	s_waitcnt lgkmcnt(0)
	v_mfma_f32_16x16x32_bf16 v[120:123], v[54:57], v[28:31], v[50:53]
	s_nop 4
	ds_read_b128 v[50:53], v229 offset:17408
	ds_read_b128 v[54:57], v229 offset:17472
	s_waitcnt lgkmcnt(1)
	v_mfma_f32_16x16x32_bf16 v[50:53], v[50:53], v[16:19], 0
	s_waitcnt lgkmcnt(0)
	v_mfma_f32_16x16x32_bf16 v[50:53], v[54:57], v[20:23], v[50:53]
	ds_read_b128 v[54:57], v229 offset:17536
	s_waitcnt lgkmcnt(0)
	v_mfma_f32_16x16x32_bf16 v[50:53], v[54:57], v[24:27], v[50:53]
	ds_read_b128 v[54:57], v229 offset:17600
	s_waitcnt lgkmcnt(0)
	v_mfma_f32_16x16x32_bf16 v[124:127], v[54:57], v[28:31], v[50:53]
	ds_read2st64_b32 v[46:47], v214 offset0:4 offset1:6
	s_nop 3
	ds_read_b128 v[50:53], v48 offset:34816
	ds_read_b128 v[54:57], v48 offset:34880
	s_waitcnt lgkmcnt(1)
	v_mfma_f32_16x16x32_bf16 v[50:53], v[50:53], v[16:19], 0
	s_waitcnt lgkmcnt(0)
	v_mfma_f32_16x16x32_bf16 v[50:53], v[54:57], v[20:23], v[50:53]
	ds_read_b128 v[54:57], v48 offset:34944
	s_waitcnt lgkmcnt(0)
	v_mfma_f32_16x16x32_bf16 v[50:53], v[54:57], v[24:27], v[50:53]
	ds_read_b128 v[54:57], v48 offset:35008
	s_waitcnt lgkmcnt(0)
	v_mfma_f32_16x16x32_bf16 v[128:131], v[54:57], v[28:31], v[50:53]
	s_nop 4
	ds_read_b128 v[50:53], v48 offset:39168
	ds_read_b128 v[54:57], v48 offset:39232
	s_waitcnt lgkmcnt(1)
	v_mfma_f32_16x16x32_bf16 v[50:53], v[50:53], v[16:19], 0
	s_waitcnt lgkmcnt(0)
	v_mfma_f32_16x16x32_bf16 v[50:53], v[54:57], v[20:23], v[50:53]
	ds_read_b128 v[54:57], v48 offset:39296
	s_waitcnt lgkmcnt(0)
	v_mfma_f32_16x16x32_bf16 v[50:53], v[54:57], v[24:27], v[50:53]
	ds_read_b128 v[54:57], v48 offset:39360
	s_waitcnt lgkmcnt(0)
	v_mfma_f32_16x16x32_bf16 v[136:139], v[54:57], v[28:31], v[50:53]
	s_nop 4
	ds_read_b128 v[50:53], v48 offset:43520
	ds_read_b128 v[54:57], v48 offset:43584
	s_waitcnt lgkmcnt(1)
; #define LAS __attribute__((address_space(3)))
; #define MFMA16(a, b, c) __builtin_amdgcn_mfma_f32_16x16x32_bf16((a), (b), (c), 0, 0, 0)
; DI void conv_image(LAS char* img, const bf16* PROJ, int b, int t0, int chan0, const float* cw, const float* cb, int item) {
;     const int cgp = item & 15, tg = item >> 4, ch = chan0 + cgp * 8, tb = t0 + tg * 8;
;     const bf16* base = slab(PROJ, (C_CX + ch) & ~63, b) + ((C_CX + ch) & 63);
;     float w[5][8], o[8][8];
; #pragma unroll
;     for (int k = 0; k < 5; ++k) { const f32x4 a = *(const f32x4*)(cw + k * 768 + ch), c = *(const f32x4*)(cw + k * 768 + ch + 4);
; #pragma unroll
;         for (int e = 0; e < 4; ++e) { w[k][e] = a[e]; w[k][4 + e] = c[e]; } }
;     { const f32x4 a = *(const f32x4*)(cb + ch), c = *(const f32x4*)(cb + ch + 4);
; #pragma unroll
;       for (int oi = 0; oi < 8; ++oi)
; #pragma unroll
;           for (int e = 0; e < 4; ++e) { o[oi][e] = a[e]; o[oi][4 + e] = c[e]; } }
; #pragma unroll
;     for (int ri = 0; ri < 12; ++ri) {
;         const int t = tb - 2 + ri;
;         u32x4 v = (u32x4){0u, 0u, 0u, 0u};
;         if (t >= 0 && t < T) v = *(const u32x4*)(base + (size_t)t * 64);
; DI void ssd_part2_unit(int u, const bf16* PROJ, const float* DT, const float* cw, const float* cb, const float* a_log_l, const float* dskip_l, const float* snw_l,
;                        const float* STATES, bf16* YC, LAS unsigned char* ldsu, int tid, int wave, int lane) {
;     ...
;     for (int combo = 0; combo < 4; ++combo) {
;         const int hh = combo >> 1;
;         const float eg = __expf(gtab[combo * 128 + lq]);
; #pragma unroll
;         for (int pt = 0; pt < 4; ++pt) {
;             f32x4 tmp = (f32x4){0.f, 0.f, 0.f, 0.f};
; #pragma unroll
;             for (int ks = 0; ks < 4; ++ks) { const bf16x8 af = *(const LAS bf16x8*)(lds + combo * (64 * IMG_PITCH) + (16 * pt + r) * IMG_PITCH + 64 * ks + 16 * g); tmp = MFMA16(af, cq[ks], tmp); }
;             acc[hh][pt] += tmp * eg;
;         }
;     }
;     __syncthreads();
;     { const int img = tid >> 8; conv_image(lds + img * IMG_BYTES, PROJ, b, t0, img * 256 + grp * 128, cw, cb, tid & 255); }
	v_mfma_f32_16x16x32_bf16 v[50:53], v[50:53], v[16:19], 0
	s_waitcnt lgkmcnt(0)
	v_mfma_f32_16x16x32_bf16 v[50:53], v[54:57], v[20:23], v[50:53]
	ds_read_b128 v[54:57], v48 offset:43648
	s_waitcnt lgkmcnt(0)
	v_mfma_f32_16x16x32_bf16 v[50:53], v[54:57], v[24:27], v[50:53]
	ds_read_b128 v[54:57], v48 offset:43712
	s_waitcnt lgkmcnt(0)
	v_mfma_f32_16x16x32_bf16 v[140:143], v[54:57], v[28:31], v[50:53]
	s_nop 4
	ds_read_b128 v[50:53], v229 offset:34816
	ds_read_b128 v[54:57], v229 offset:34880
	s_waitcnt lgkmcnt(1)
	v_mfma_f32_16x16x32_bf16 v[50:53], v[50:53], v[16:19], 0
	s_waitcnt lgkmcnt(0)
	v_mfma_f32_16x16x32_bf16 v[50:53], v[54:57], v[20:23], v[50:53]
	ds_read_b128 v[54:57], v229 offset:34944
	s_waitcnt lgkmcnt(0)
	v_mfma_f32_16x16x32_bf16 v[50:53], v[54:57], v[24:27], v[50:53]
	ds_read_b128 v[54:57], v229 offset:35008
	s_waitcnt lgkmcnt(0)
	v_mfma_f32_16x16x32_bf16 v[144:147], v[54:57], v[28:31], v[50:53]
	s_nop 4
	ds_read_b128 v[50:53], v48 offset:52224
	ds_read_b128 v[54:57], v48 offset:52288
	s_waitcnt lgkmcnt(1)
	v_mfma_f32_16x16x32_bf16 v[50:53], v[50:53], v[16:19], 0
	s_waitcnt lgkmcnt(0)
	v_mfma_f32_16x16x32_bf16 v[50:53], v[54:57], v[20:23], v[50:53]
	ds_read_b128 v[54:57], v48 offset:52352
	s_waitcnt lgkmcnt(0)
	v_mfma_f32_16x16x32_bf16 v[50:53], v[54:57], v[24:27], v[50:53]
	ds_read_b128 v[54:57], v48 offset:52416
	s_waitcnt lgkmcnt(0)
	v_mfma_f32_16x16x32_bf16 v[152:155], v[54:57], v[28:31], v[50:53]
	s_nop 4
	ds_read_b128 v[50:53], v48 offset:56576
	ds_read_b128 v[54:57], v48 offset:56640
	s_waitcnt lgkmcnt(1)
	v_mfma_f32_16x16x32_bf16 v[50:53], v[50:53], v[16:19], 0
	s_waitcnt lgkmcnt(0)
	v_mfma_f32_16x16x32_bf16 v[50:53], v[54:57], v[20:23], v[50:53]
	ds_read_b128 v[54:57], v48 offset:56704
	s_waitcnt lgkmcnt(0)
	v_mfma_f32_16x16x32_bf16 v[50:53], v[54:57], v[24:27], v[50:53]
	ds_read_b128 v[54:57], v48 offset:56768
	s_waitcnt lgkmcnt(0)
	v_mfma_f32_16x16x32_bf16 v[156:159], v[54:57], v[28:31], v[50:53]
	s_nop 4
	ds_read_b128 v[50:53], v48 offset:60928
	ds_read_b128 v[54:57], v48 offset:60992
	s_waitcnt lgkmcnt(1)
	v_mfma_f32_16x16x32_bf16 v[50:53], v[50:53], v[16:19], 0
	s_waitcnt lgkmcnt(0)
	v_mfma_f32_16x16x32_bf16 v[50:53], v[54:57], v[20:23], v[50:53]
	ds_read_b128 v[54:57], v48 offset:61056
	s_waitcnt lgkmcnt(0)
	v_mfma_f32_16x16x32_bf16 v[50:53], v[54:57], v[24:27], v[50:53]
	ds_read_b128 v[54:57], v48 offset:61120
	s_waitcnt lgkmcnt(0)
	v_mfma_f32_16x16x32_bf16 v[172:175], v[54:57], v[28:31], v[50:53]
	s_nop 4
	ds_read_b128 v[48:51], v229 offset:52224
	ds_read_b128 v[52:55], v229 offset:52288
	s_waitcnt lgkmcnt(1)
	v_mfma_f32_16x16x32_bf16 v[48:51], v[48:51], v[16:19], 0
	s_waitcnt lgkmcnt(0)
	v_mfma_f32_16x16x32_bf16 v[48:51], v[52:55], v[20:23], v[48:51]
	ds_read_b128 v[52:55], v229 offset:52352
	s_waitcnt lgkmcnt(0)
	v_mfma_f32_16x16x32_bf16 v[48:51], v[52:55], v[24:27], v[48:51]
	ds_read_b128 v[52:55], v229 offset:52416
	s_waitcnt lgkmcnt(0)
	s_barrier
	v_mfma_f32_16x16x32_bf16 v[160:163], v[52:55], v[28:31], v[48:51]
	s_nop 3
	v_or_b32_e32 v48, s34, v217
	v_ashrrev_i32_e32 v49, 31, v48
	v_lshlrev_b64 v[50:51], 2, v[48:49]
	v_lshl_add_u64 v[76:77], s[26:27], 0, v[50:51]
	v_add_co_u32_e32 v62, vcc, 0x1000, v76
	v_lshl_add_u64 v[60:61], v[76:77], 0, s[0:1]
	s_nop 0
	v_addc_co_u32_e32 v63, vcc, 0, v77, vcc
	s_mov_b64 s[0:1], 0x2400
	v_add_co_u32_e32 v66, vcc, 0x2000, v76
	v_lshl_add_u64 v[64:65], v[76:77], 0, s[0:1]
	s_nop 0
	v_addc_co_u32_e32 v67, vcc, 0, v77, vcc
	s_mov_b64 s[0:1], 0x3000
	global_load_dwordx4 v[52:55], v[76:77], off offset:16
	global_load_dwordx4 v[68:71], v[76:77], off
	global_load_dwordx4 v[56:59], v[76:77], off offset:3088
	global_load_dwordx4 v[72:75], v[76:77], off offset:3072
	v_lshl_add_u64 v[78:79], v[76:77], 0, s[0:1]
	v_add_co_u32_e32 v76, vcc, 0x3000, v76
	v_lshl_add_u64 v[50:51], s[52:53], 0, v[50:51]
	s_nop 0
	v_addc_co_u32_e32 v77, vcc, 0, v77, vcc
	global_load_dwordx4 v[84:87], v[62:63], off offset:2048
	s_nop 0
	global_load_dwordx4 v[60:63], v[60:61], off offset:16
	s_nop 0
	global_load_dwordx4 v[88:91], v[66:67], off offset:1024
	s_nop 0
	global_load_dwordx4 v[64:67], v[64:65], off offset:16
	s_nop 0
	global_load_dwordx4 v[92:95], v[76:77], off
	s_nop 0
	global_load_dwordx4 v[76:79], v[78:79], off offset:16
	s_nop 0
	global_load_dwordx4 v[80:83], v[50:51], off offset:16
	global_load_dwordx4 v[96:99], v[50:51], off
	s_movk_i32 s0, 0x7ff
	v_cmp_gt_u32_e32 vcc, s24, v102
	v_cmp_lt_u32_e64 s[0:1], s0, v102
	s_and_saveexec_b64 s[60:61], s[0:1]
	s_xor_b64 s[0:1], exec, s[60:61]
	v_lshlrev_b32_e32 v50, 6, v102
	s_or_saveexec_b64 s[0:1], s[0:1]
	v_add_u32_e32 v48, 0x900, v48
	v_ashrrev_i32_e32 v48, 6, v48
	v_ashrrev_i32_e32 v49, 31, v48
	s_ashr_i32 s95, s94, 31
	v_lshlrev_b64 v[48:49], 21, v[48:49]
	s_lshl_b64 s[62:63], s[94:95], 18
	v_lshl_add_u64 v[48:49], s[10:11], 0, v[48:49]
	v_lshl_add_u64 v[48:49], v[48:49], 0, s[62:63]
	v_mov_b32_e32 v101, v189
	v_lshl_add_u64 v[48:49], v[48:49], 0, v[100:101]
	v_mov_b32_e32 v168, 0
	v_mov_b32_e32 v164, 0
	v_mov_b32_e32 v165, 0
	v_mov_b32_e32 v166, 0
	v_mov_b32_e32 v167, 0
	s_xor_b64 exec, exec, s[0:1]
	s_cbranch_execz .LBB0_507
	v_lshl_add_u64 v[50:51], v[188:189], 1, v[48:49]
	global_load_dwordx4 v[164:167], v[50:51], off
	v_mov_b32_e32 v50, v188
